# pooling items: wide-window and narrow-window waves paired on each SIMD (channel half chosen by wave ^ wave>>2)
# speedup vs baseline: 1.0052x; 1.0034x over previous
; __device__ __forceinline__ float bf_lo(unsigned w) { return __uint_as_float(w << 16); }
; __device__ __forceinline__ float bf_hi(unsigned w) { return __uint_as_float(w & 0xffff0000u); }
; template <int W> __device__ __forceinline__ void pool_item(const bfu* u, bfu* pooled, int tb) {
;     v4u r[W + 7];
; #pragma unroll
;     for (int j = 0; j < W + 7; ++j) { const int t = tb - (W - 1) + j; r[j] = (t >= 0) ? *(const v4u*)(u + (size_t)t * 1024) : (v4u){0u, 0u, 0u, 0u}; }
;     float a[8];
; #pragma unroll
;     for (int e = 0; e < 8; ++e) a[e] = 0.f;
; #pragma unroll
;     for (int j = 0; j < W - 1; ++j) { a[0] += pg8::bf_lo(r[j].x); a[1] += pg8::bf_hi(r[j].x); a[2] += pg8::bf_lo(r[j].y); a[3] += pg8::bf_hi(r[j].y); a[4] += pg8::bf_lo(r[j].z); a[5] += pg8::bf_hi(r[j].z); a[6] += pg8::bf_lo(r[j].w); a[7] += pg8::bf_hi(r[j].w); }
; __global__ void __launch_bounds__(NWAVES * 64, 2) fwd_megakernel(Args args) {
;     ...
;             if (n >= 768u) {
;                 const int pc = (int)(n - 768u);
; #pragma unroll 1
;                 for (int k2 = 0; k2 < 2; ++k2) { const int i = pc * 1024 + k2 * 512 + (int)threadIdx.x; const int ch = i & 127, tb = (i >> 7) * 8, gidx = ch >> 5;
;                     const bfu* up = Ub + ch * 8; bfu* pp = AB2 + 1024 + ch * 8;
;                     if (gidx == 0) pool_item<2>(up, pp, tb); else if (gidx == 1) pool_item<4>(up, pp, tb); else if (gidx == 2) pool_item<8>(up, pp, tb); else pool_item<16>(up, pp, tb); }
.LBB0_338:
	s_and_b64 vcc, exec, s[0:1]
	s_cbranch_vccz .LBB0_472
	s_cmpk_eq_u32 s86, 0x300
	s_cbranch_scc1 .Lpool_orig
	v_readfirstlane_b32 s62, v227
	s_mov_b32 s68, 0
	s_mov_b32 s69, -1
	s_mov_b32 s67, 0
	s_mov_b32 s71, 0
	s_lshr_b32 s62, s62, 6
	s_and_b32 s63, s62, 1
	s_lshr_b32 s0, s62, 2
	s_xor_b32 s63, s63, s0
	s_lshr_b32 s64, s62, 1
	s_add_i32 s65, s86, 0xfffffd00
	s_lshl_b32 s65, s65, 2
	s_add_i32 s65, s65, s64
	s_lshl_b32 s65, s65, 4
	s_lshl_b32 s70, s65, 12
	s_add_i32 s66, s65, -15
	s_lshl_b32 s66, s66, 11
	s_lshl_b32 s1, s63, 11
	s_sub_i32 s1, s1, 0x400
	s_mul_i32 s1, s1, s0
	s_add_i32 s66, s66, s1
	s_add_i32 s70, s70, s1
	s_cmp_eq_u32 s63, 0
	s_cbranch_scc1 .Lpool_even
	v_lshl_add_u64 v[0:1], v[222:223], 0, s[66:67]
	global_load_dwordx4 v[0:3], v[0:1], off
	s_add_u32 s66, s66, 0x800
	v_lshl_add_u64 v[4:5], v[222:223], 0, s[66:67]
	global_load_dwordx4 v[4:7], v[4:5], off
	s_add_u32 s66, s66, 0x800
	v_lshl_add_u64 v[8:9], v[222:223], 0, s[66:67]
	global_load_dwordx4 v[8:11], v[8:9], off
	s_add_u32 s66, s66, 0x800
	v_lshl_add_u64 v[12:13], v[222:223], 0, s[66:67]
	global_load_dwordx4 v[12:15], v[12:13], off
	s_add_u32 s66, s66, 0x800
	v_lshl_add_u64 v[16:17], v[222:223], 0, s[66:67]
	global_load_dwordx4 v[16:19], v[16:17], off
	s_add_u32 s66, s66, 0x800
	v_lshl_add_u64 v[20:21], v[222:223], 0, s[66:67]
	global_load_dwordx4 v[20:23], v[20:21], off
	s_add_u32 s66, s66, 0x800
	v_lshl_add_u64 v[24:25], v[222:223], 0, s[66:67]
	global_load_dwordx4 v[24:27], v[24:25], off
	s_add_u32 s66, s66, 0x800
	v_lshl_add_u64 v[28:29], v[222:223], 0, s[66:67]
	global_load_dwordx4 v[28:31], v[28:29], off
	s_add_u32 s66, s66, 0x800
	v_lshl_add_u64 v[32:33], v[222:223], 0, s[66:67]
	global_load_dwordx4 v[32:35], v[32:33], off
	s_add_u32 s66, s66, 0x800
	v_lshl_add_u64 v[36:37], v[222:223], 0, s[66:67]
	global_load_dwordx4 v[36:39], v[36:37], off
	s_add_u32 s66, s66, 0x800
	v_lshl_add_u64 v[40:41], v[222:223], 0, s[66:67]
	global_load_dwordx4 v[40:43], v[40:41], off
	s_add_u32 s66, s66, 0x800
	v_lshl_add_u64 v[44:45], v[222:223], 0, s[66:67]
	global_load_dwordx4 v[44:47], v[44:45], off
	s_add_u32 s66, s66, 0x800
	v_lshl_add_u64 v[48:49], v[222:223], 0, s[66:67]
	global_load_dwordx4 v[48:51], v[48:49], off
	s_add_u32 s66, s66, 0x800
	v_lshl_add_u64 v[52:53], v[222:223], 0, s[66:67]
	global_load_dwordx4 v[52:55], v[52:53], off
	s_add_u32 s66, s66, 0x800
	v_lshl_add_u64 v[56:57], v[222:223], 0, s[66:67]
	global_load_dwordx4 v[56:59], v[56:57], off
	s_add_u32 s66, s66, 0x800
	v_lshl_add_u64 v[60:61], v[222:223], 0, s[66:67]
	global_load_dwordx4 v[60:63], v[60:61], off
	s_add_u32 s66, s66, 0x800
	v_lshl_add_u64 v[64:65], v[222:223], 0, s[66:67]
	global_load_dwordx4 v[64:67], v[64:65], off
	s_add_u32 s66, s66, 0x800
	v_lshl_add_u64 v[68:69], v[222:223], 0, s[66:67]
	global_load_dwordx4 v[68:71], v[68:69], off
	s_add_u32 s66, s66, 0x800
	v_lshl_add_u64 v[72:73], v[222:223], 0, s[66:67]
	global_load_dwordx4 v[72:75], v[72:73], off
	s_add_u32 s66, s66, 0x800
	v_lshl_add_u64 v[76:77], v[222:223], 0, s[66:67]
	global_load_dwordx4 v[76:79], v[76:77], off
	s_add_u32 s66, s66, 0x800
	v_lshl_add_u64 v[80:81], v[222:223], 0, s[66:67]
	global_load_dwordx4 v[80:83], v[80:81], off
	s_add_u32 s66, s66, 0x800
	v_lshl_add_u64 v[84:85], v[222:223], 0, s[66:67]
	global_load_dwordx4 v[84:87], v[84:85], off
	s_add_u32 s66, s66, 0x800
	v_lshl_add_u64 v[88:89], v[222:223], 0, s[66:67]
	global_load_dwordx4 v[88:91], v[88:89], off
	s_add_u32 s66, s66, 0x800
	v_lshl_add_u64 v[92:93], v[222:223], 0, s[66:67]
	global_load_dwordx4 v[92:95], v[92:93], off
	s_add_u32 s66, s66, 0x800
	v_lshl_add_u64 v[96:97], v[222:223], 0, s[66:67]
	global_load_dwordx4 v[96:99], v[96:97], off
	s_add_u32 s66, s66, 0x800
	v_lshl_add_u64 v[100:101], v[222:223], 0, s[66:67]
	global_load_dwordx4 v[100:103], v[100:101], off
	s_add_u32 s66, s66, 0x800
	v_lshl_add_u64 v[104:105], v[222:223], 0, s[66:67]
	global_load_dwordx4 v[104:107], v[104:105], off
	s_add_u32 s66, s66, 0x800
	v_lshl_add_u64 v[108:109], v[222:223], 0, s[66:67]
	global_load_dwordx4 v[108:111], v[108:109], off
	s_add_u32 s66, s66, 0x800
	v_lshl_add_u64 v[112:113], v[222:223], 0, s[66:67]
	global_load_dwordx4 v[112:115], v[112:113], off
	s_add_u32 s66, s66, 0x800
	v_lshl_add_u64 v[116:117], v[222:223], 0, s[66:67]
	global_load_dwordx4 v[116:119], v[116:117], off
	s_add_u32 s66, s66, 0x800
	v_lshl_add_u64 v[120:121], v[222:223], 0, s[66:67]
	global_load_dwordx4 v[120:123], v[120:121], off
	s_add_u32 s66, s66, 0x800
	s_mov_b64 exec, -1
	v_mov_b32_e32 v148, 0x3e000000
	v_mov_b32_e32 v149, 0x3e000000
	v_mov_b32_e32 v124, 0
	v_mov_b32_e32 v125, 0
	v_mov_b32_e32 v126, 0
	v_mov_b32_e32 v127, 0
	v_mov_b32_e32 v128, 0
	v_mov_b32_e32 v129, 0
	v_mov_b32_e32 v130, 0
	v_mov_b32_e32 v131, 0
	s_mov_b64 exec, s[68:69]
	v_mov_b32_e32 v148, 0x3d800000
	v_mov_b32_e32 v149, 0x3d800000
	s_waitcnt vmcnt(30)
	v_lshlrev_b32_e32 v132, 16, v0
	v_and_b32_e32 v133, 0xffff0000, v0
	v_lshlrev_b32_e32 v134, 16, v1
	v_and_b32_e32 v135, 0xffff0000, v1
	v_lshlrev_b32_e32 v136, 16, v2
	v_and_b32_e32 v137, 0xffff0000, v2
	v_lshlrev_b32_e32 v138, 16, v3
	v_and_b32_e32 v139, 0xffff0000, v3
	v_pk_add_f32 v[124:125], v[124:125], v[132:133]
	v_pk_add_f32 v[126:127], v[126:127], v[134:135]
	v_pk_add_f32 v[128:129], v[128:129], v[136:137]
	v_pk_add_f32 v[130:131], v[130:131], v[138:139]
	s_waitcnt vmcnt(29)
	v_lshlrev_b32_e32 v132, 16, v4
	v_and_b32_e32 v133, 0xffff0000, v4
	v_lshlrev_b32_e32 v134, 16, v5
	v_and_b32_e32 v135, 0xffff0000, v5
	v_lshlrev_b32_e32 v136, 16, v6
	v_and_b32_e32 v137, 0xffff0000, v6
	v_lshlrev_b32_e32 v138, 16, v7
	v_and_b32_e32 v139, 0xffff0000, v7
	v_pk_add_f32 v[124:125], v[124:125], v[132:133]
	v_pk_add_f32 v[126:127], v[126:127], v[134:135]
	v_pk_add_f32 v[128:129], v[128:129], v[136:137]
	v_pk_add_f32 v[130:131], v[130:131], v[138:139]
	s_waitcnt vmcnt(28)
; __device__ __forceinline__ float bf_lo(unsigned w) { return __uint_as_float(w << 16); }
; __device__ __forceinline__ float bf_hi(unsigned w) { return __uint_as_float(w & 0xffff0000u); }
; template <int W> __device__ __forceinline__ void pool_item(const bfu* u, bfu* pooled, int tb) {
;     ...
;     for (int j = 0; j < W - 1; ++j) { a[0] += pg8::bf_lo(r[j].x); a[1] += pg8::bf_hi(r[j].x); a[2] += pg8::bf_lo(r[j].y); a[3] += pg8::bf_hi(r[j].y); a[4] += pg8::bf_lo(r[j].z); a[5] += pg8::bf_hi(r[j].z); a[6] += pg8::bf_lo(r[j].w); a[7] += pg8::bf_hi(r[j].w); }
	v_lshlrev_b32_e32 v132, 16, v8
	v_and_b32_e32 v133, 0xffff0000, v8
	v_lshlrev_b32_e32 v134, 16, v9
	v_and_b32_e32 v135, 0xffff0000, v9
	v_lshlrev_b32_e32 v136, 16, v10
	v_and_b32_e32 v137, 0xffff0000, v10
	v_lshlrev_b32_e32 v138, 16, v11
	v_and_b32_e32 v139, 0xffff0000, v11
	v_pk_add_f32 v[124:125], v[124:125], v[132:133]
	v_pk_add_f32 v[126:127], v[126:127], v[134:135]
	v_pk_add_f32 v[128:129], v[128:129], v[136:137]
	v_pk_add_f32 v[130:131], v[130:131], v[138:139]
	s_waitcnt vmcnt(27)
	v_lshlrev_b32_e32 v132, 16, v12
	v_and_b32_e32 v133, 0xffff0000, v12
	v_lshlrev_b32_e32 v134, 16, v13
	v_and_b32_e32 v135, 0xffff0000, v13
	v_lshlrev_b32_e32 v136, 16, v14
	v_and_b32_e32 v137, 0xffff0000, v14
	v_lshlrev_b32_e32 v138, 16, v15
	v_and_b32_e32 v139, 0xffff0000, v15
	v_pk_add_f32 v[124:125], v[124:125], v[132:133]
	v_pk_add_f32 v[126:127], v[126:127], v[134:135]
	v_pk_add_f32 v[128:129], v[128:129], v[136:137]
	v_pk_add_f32 v[130:131], v[130:131], v[138:139]
	s_waitcnt vmcnt(26)
	v_lshlrev_b32_e32 v132, 16, v16
	v_and_b32_e32 v133, 0xffff0000, v16
	v_lshlrev_b32_e32 v134, 16, v17
	v_and_b32_e32 v135, 0xffff0000, v17
	v_lshlrev_b32_e32 v136, 16, v18
	v_and_b32_e32 v137, 0xffff0000, v18
	v_lshlrev_b32_e32 v138, 16, v19
	v_and_b32_e32 v139, 0xffff0000, v19
	v_pk_add_f32 v[124:125], v[124:125], v[132:133]
	v_pk_add_f32 v[126:127], v[126:127], v[134:135]
	v_pk_add_f32 v[128:129], v[128:129], v[136:137]
	v_pk_add_f32 v[130:131], v[130:131], v[138:139]
	s_waitcnt vmcnt(25)
	v_lshlrev_b32_e32 v132, 16, v20
	v_and_b32_e32 v133, 0xffff0000, v20
	v_lshlrev_b32_e32 v134, 16, v21
	v_and_b32_e32 v135, 0xffff0000, v21
	v_lshlrev_b32_e32 v136, 16, v22
	v_and_b32_e32 v137, 0xffff0000, v22
	v_lshlrev_b32_e32 v138, 16, v23
	v_and_b32_e32 v139, 0xffff0000, v23
	v_pk_add_f32 v[124:125], v[124:125], v[132:133]
	v_pk_add_f32 v[126:127], v[126:127], v[134:135]
	v_pk_add_f32 v[128:129], v[128:129], v[136:137]
	v_pk_add_f32 v[130:131], v[130:131], v[138:139]
	s_waitcnt vmcnt(24)
	v_lshlrev_b32_e32 v132, 16, v24
	v_and_b32_e32 v133, 0xffff0000, v24
	v_lshlrev_b32_e32 v134, 16, v25
	v_and_b32_e32 v135, 0xffff0000, v25
	v_lshlrev_b32_e32 v136, 16, v26
	v_and_b32_e32 v137, 0xffff0000, v26
	v_lshlrev_b32_e32 v138, 16, v27
	v_and_b32_e32 v139, 0xffff0000, v27
	v_pk_add_f32 v[124:125], v[124:125], v[132:133]
	v_pk_add_f32 v[126:127], v[126:127], v[134:135]
	v_pk_add_f32 v[128:129], v[128:129], v[136:137]
	v_pk_add_f32 v[130:131], v[130:131], v[138:139]
	s_waitcnt vmcnt(23)
	v_lshlrev_b32_e32 v132, 16, v28
	v_and_b32_e32 v133, 0xffff0000, v28
	v_lshlrev_b32_e32 v134, 16, v29
	v_and_b32_e32 v135, 0xffff0000, v29
	v_lshlrev_b32_e32 v136, 16, v30
	v_and_b32_e32 v137, 0xffff0000, v30
	v_lshlrev_b32_e32 v138, 16, v31
	v_and_b32_e32 v139, 0xffff0000, v31
	v_pk_add_f32 v[124:125], v[124:125], v[132:133]
	v_pk_add_f32 v[126:127], v[126:127], v[134:135]
	v_pk_add_f32 v[128:129], v[128:129], v[136:137]
	v_pk_add_f32 v[130:131], v[130:131], v[138:139]
	s_mov_b64 exec, -1
	s_waitcnt vmcnt(22)
	v_lshlrev_b32_e32 v132, 16, v32
	v_and_b32_e32 v133, 0xffff0000, v32
	v_lshlrev_b32_e32 v134, 16, v33
	v_and_b32_e32 v135, 0xffff0000, v33
	v_lshlrev_b32_e32 v136, 16, v34
	v_and_b32_e32 v137, 0xffff0000, v34
	v_lshlrev_b32_e32 v138, 16, v35
	v_and_b32_e32 v139, 0xffff0000, v35
	v_pk_add_f32 v[124:125], v[124:125], v[132:133]
	v_pk_add_f32 v[126:127], v[126:127], v[134:135]
	v_pk_add_f32 v[128:129], v[128:129], v[136:137]
	v_pk_add_f32 v[130:131], v[130:131], v[138:139]
	s_waitcnt vmcnt(21)
	v_lshlrev_b32_e32 v132, 16, v36
	v_and_b32_e32 v133, 0xffff0000, v36
	v_lshlrev_b32_e32 v134, 16, v37
	v_and_b32_e32 v135, 0xffff0000, v37
	v_lshlrev_b32_e32 v136, 16, v38
	v_and_b32_e32 v137, 0xffff0000, v38
	v_lshlrev_b32_e32 v138, 16, v39
	v_and_b32_e32 v139, 0xffff0000, v39
	v_pk_add_f32 v[124:125], v[124:125], v[132:133]
	v_pk_add_f32 v[126:127], v[126:127], v[134:135]
	v_pk_add_f32 v[128:129], v[128:129], v[136:137]
	v_pk_add_f32 v[130:131], v[130:131], v[138:139]
	s_waitcnt vmcnt(20)
	v_lshlrev_b32_e32 v132, 16, v40
	v_and_b32_e32 v133, 0xffff0000, v40
	v_lshlrev_b32_e32 v134, 16, v41
	v_and_b32_e32 v135, 0xffff0000, v41
	v_lshlrev_b32_e32 v136, 16, v42
	v_and_b32_e32 v137, 0xffff0000, v42
	v_lshlrev_b32_e32 v138, 16, v43
	v_and_b32_e32 v139, 0xffff0000, v43
	v_pk_add_f32 v[124:125], v[124:125], v[132:133]
	v_pk_add_f32 v[126:127], v[126:127], v[134:135]
	v_pk_add_f32 v[128:129], v[128:129], v[136:137]
	v_pk_add_f32 v[130:131], v[130:131], v[138:139]
	s_waitcnt vmcnt(19)
	v_lshlrev_b32_e32 v132, 16, v44
	v_and_b32_e32 v133, 0xffff0000, v44
	v_lshlrev_b32_e32 v134, 16, v45
	v_and_b32_e32 v135, 0xffff0000, v45
	v_lshlrev_b32_e32 v136, 16, v46
	v_and_b32_e32 v137, 0xffff0000, v46
	v_lshlrev_b32_e32 v138, 16, v47
	v_and_b32_e32 v139, 0xffff0000, v47
	v_pk_add_f32 v[124:125], v[124:125], v[132:133]
	v_pk_add_f32 v[126:127], v[126:127], v[134:135]
	v_pk_add_f32 v[128:129], v[128:129], v[136:137]
	v_pk_add_f32 v[130:131], v[130:131], v[138:139]
	s_waitcnt vmcnt(18)
	v_lshlrev_b32_e32 v132, 16, v48
	v_and_b32_e32 v133, 0xffff0000, v48
	v_lshlrev_b32_e32 v134, 16, v49
	v_and_b32_e32 v135, 0xffff0000, v49
	v_lshlrev_b32_e32 v136, 16, v50
	v_and_b32_e32 v137, 0xffff0000, v50
	v_lshlrev_b32_e32 v138, 16, v51
	v_and_b32_e32 v139, 0xffff0000, v51
	v_pk_add_f32 v[124:125], v[124:125], v[132:133]
	v_pk_add_f32 v[126:127], v[126:127], v[134:135]
	v_pk_add_f32 v[128:129], v[128:129], v[136:137]
	v_pk_add_f32 v[130:131], v[130:131], v[138:139]
	s_waitcnt vmcnt(17)
; __device__ __forceinline__ float bf_lo(unsigned w) { return __uint_as_float(w << 16); }
; __device__ __forceinline__ float bf_hi(unsigned w) { return __uint_as_float(w & 0xffff0000u); }
; __device__ __forceinline__ unsigned pk2(float lo, float hi) { return f2bf(lo) | (f2bf(hi) << 16); }
; template <int W> __device__ __forceinline__ void pool_item(const bfu* u, bfu* pooled, int tb) {
;     ...
;     for (int k = 0; k < 8; ++k) {
;         const v4u c = r[W - 1 + k]; const int t = tb + k;
;         const float cv[8] = {pg8::bf_lo(c.x), pg8::bf_hi(c.x), pg8::bf_lo(c.y), pg8::bf_hi(c.y), pg8::bf_lo(c.z), pg8::bf_hi(c.z), pg8::bf_lo(c.w), pg8::bf_hi(c.w)};
; #pragma unroll
;         for (int e = 0; e < 8; ++e) a[e] += cv[e];
;         const float inv = 1.f / (float)((t + 1) < W ? (t + 1) : W);
;         v4u o; o.x = pk2(a[0] * inv - cv[0], a[1] * inv - cv[1]); o.y = pk2(a[2] * inv - cv[2], a[3] * inv - cv[3]); o.z = pk2(a[4] * inv - cv[4], a[5] * inv - cv[5]); o.w = pk2(a[6] * inv - cv[6], a[7] * inv - cv[7]);
;         *(v4u*)(pooled + (size_t)t * 2048) = o;
;         const v4u d = r[k];
;         a[0] -= pg8::bf_lo(d.x); a[1] -= pg8::bf_hi(d.x); a[2] -= pg8::bf_lo(d.y); a[3] -= pg8::bf_hi(d.y); a[4] -= pg8::bf_lo(d.z); a[5] -= pg8::bf_hi(d.z); a[6] -= pg8::bf_lo(d.w); a[7] -= pg8::bf_hi(d.w);
;     }
	v_lshlrev_b32_e32 v132, 16, v52
	v_and_b32_e32 v133, 0xffff0000, v52
	v_lshlrev_b32_e32 v134, 16, v53
	v_and_b32_e32 v135, 0xffff0000, v53
	v_lshlrev_b32_e32 v136, 16, v54
	v_and_b32_e32 v137, 0xffff0000, v54
	v_lshlrev_b32_e32 v138, 16, v55
	v_and_b32_e32 v139, 0xffff0000, v55
	v_pk_add_f32 v[124:125], v[124:125], v[132:133]
	v_pk_add_f32 v[126:127], v[126:127], v[134:135]
	v_pk_add_f32 v[128:129], v[128:129], v[136:137]
	v_pk_add_f32 v[130:131], v[130:131], v[138:139]
	s_waitcnt vmcnt(16)
	v_lshlrev_b32_e32 v132, 16, v56
	v_and_b32_e32 v133, 0xffff0000, v56
	v_lshlrev_b32_e32 v134, 16, v57
	v_and_b32_e32 v135, 0xffff0000, v57
	v_lshlrev_b32_e32 v136, 16, v58
	v_and_b32_e32 v137, 0xffff0000, v58
	v_lshlrev_b32_e32 v138, 16, v59
	v_and_b32_e32 v139, 0xffff0000, v59
	v_pk_add_f32 v[124:125], v[124:125], v[132:133]
	v_pk_add_f32 v[126:127], v[126:127], v[134:135]
	v_pk_add_f32 v[128:129], v[128:129], v[136:137]
	v_pk_add_f32 v[130:131], v[130:131], v[138:139]
	s_waitcnt vmcnt(15)
	v_lshlrev_b32_e32 v132, 16, v60
	v_and_b32_e32 v133, 0xffff0000, v60
	v_lshlrev_b32_e32 v134, 16, v61
	v_and_b32_e32 v135, 0xffff0000, v61
	v_lshlrev_b32_e32 v136, 16, v62
	v_and_b32_e32 v137, 0xffff0000, v62
	v_lshlrev_b32_e32 v138, 16, v63
	v_and_b32_e32 v139, 0xffff0000, v63
	v_pk_add_f32 v[124:125], v[124:125], v[132:133]
	v_pk_add_f32 v[126:127], v[126:127], v[134:135]
	v_pk_add_f32 v[128:129], v[128:129], v[136:137]
	v_pk_add_f32 v[130:131], v[130:131], v[138:139]
	v_pk_fma_f32 v[132:133], v[148:149], v[124:125], v[132:133] neg_lo:[0,0,1] neg_hi:[0,0,1]
	v_pk_fma_f32 v[134:135], v[148:149], v[126:127], v[134:135] neg_lo:[0,0,1] neg_hi:[0,0,1]
	v_pk_fma_f32 v[136:137], v[148:149], v[128:129], v[136:137] neg_lo:[0,0,1] neg_hi:[0,0,1]
	v_pk_fma_f32 v[138:139], v[148:149], v[130:131], v[138:139] neg_lo:[0,0,1] neg_hi:[0,0,1]
	v_cvt_pk_bf16_f32 v140, v132, v133
	v_cvt_pk_bf16_f32 v141, v134, v135
	v_cvt_pk_bf16_f32 v142, v136, v137
	v_cvt_pk_bf16_f32 v143, v138, v139
	v_lshl_add_u64 v[150:151], v[224:225], 0, s[70:71]
	s_add_u32 s70, s70, 0x1000
	global_store_dwordx4 v[150:151], v[140:143], off
	v_cndmask_b32_e64 v144, v32, v0, s[68:69]
	v_cndmask_b32_e64 v145, v33, v1, s[68:69]
	v_cndmask_b32_e64 v146, v34, v2, s[68:69]
	v_cndmask_b32_e64 v147, v35, v3, s[68:69]
	v_lshlrev_b32_e32 v132, 16, v144
	v_and_b32_e32 v133, 0xffff0000, v144
	v_lshlrev_b32_e32 v134, 16, v145
	v_and_b32_e32 v135, 0xffff0000, v145
	v_lshlrev_b32_e32 v136, 16, v146
	v_and_b32_e32 v137, 0xffff0000, v146
	v_lshlrev_b32_e32 v138, 16, v147
	v_and_b32_e32 v139, 0xffff0000, v147
	v_pk_add_f32 v[124:125], v[124:125], v[132:133] neg_lo:[0,1] neg_hi:[0,1]
	v_pk_add_f32 v[126:127], v[126:127], v[134:135] neg_lo:[0,1] neg_hi:[0,1]
	v_pk_add_f32 v[128:129], v[128:129], v[136:137] neg_lo:[0,1] neg_hi:[0,1]
	v_pk_add_f32 v[130:131], v[130:131], v[138:139] neg_lo:[0,1] neg_hi:[0,1]
	s_waitcnt vmcnt(15)
	v_lshlrev_b32_e32 v132, 16, v64
	v_and_b32_e32 v133, 0xffff0000, v64
	v_lshlrev_b32_e32 v134, 16, v65
	v_and_b32_e32 v135, 0xffff0000, v65
	v_lshlrev_b32_e32 v136, 16, v66
	v_and_b32_e32 v137, 0xffff0000, v66
	v_lshlrev_b32_e32 v138, 16, v67
	v_and_b32_e32 v139, 0xffff0000, v67
	v_pk_add_f32 v[124:125], v[124:125], v[132:133]
	v_pk_add_f32 v[126:127], v[126:127], v[134:135]
	v_pk_add_f32 v[128:129], v[128:129], v[136:137]
	v_pk_add_f32 v[130:131], v[130:131], v[138:139]
	v_pk_fma_f32 v[132:133], v[148:149], v[124:125], v[132:133] neg_lo:[0,0,1] neg_hi:[0,0,1]
	v_pk_fma_f32 v[134:135], v[148:149], v[126:127], v[134:135] neg_lo:[0,0,1] neg_hi:[0,0,1]
	v_pk_fma_f32 v[136:137], v[148:149], v[128:129], v[136:137] neg_lo:[0,0,1] neg_hi:[0,0,1]
	v_pk_fma_f32 v[138:139], v[148:149], v[130:131], v[138:139] neg_lo:[0,0,1] neg_hi:[0,0,1]
	v_cvt_pk_bf16_f32 v140, v132, v133
	v_cvt_pk_bf16_f32 v141, v134, v135
	v_cvt_pk_bf16_f32 v142, v136, v137
	v_cvt_pk_bf16_f32 v143, v138, v139
	v_lshl_add_u64 v[150:151], v[224:225], 0, s[70:71]
	s_add_u32 s70, s70, 0x1000
	global_store_dwordx4 v[150:151], v[140:143], off
	v_cndmask_b32_e64 v144, v36, v4, s[68:69]
	v_cndmask_b32_e64 v145, v37, v5, s[68:69]
	v_cndmask_b32_e64 v146, v38, v6, s[68:69]
	v_cndmask_b32_e64 v147, v39, v7, s[68:69]
	v_lshlrev_b32_e32 v132, 16, v144
	v_and_b32_e32 v133, 0xffff0000, v144
	v_lshlrev_b32_e32 v134, 16, v145
	v_and_b32_e32 v135, 0xffff0000, v145
	v_lshlrev_b32_e32 v136, 16, v146
	v_and_b32_e32 v137, 0xffff0000, v146
	v_lshlrev_b32_e32 v138, 16, v147
	v_and_b32_e32 v139, 0xffff0000, v147
	v_pk_add_f32 v[124:125], v[124:125], v[132:133] neg_lo:[0,1] neg_hi:[0,1]
	v_pk_add_f32 v[126:127], v[126:127], v[134:135] neg_lo:[0,1] neg_hi:[0,1]
	v_pk_add_f32 v[128:129], v[128:129], v[136:137] neg_lo:[0,1] neg_hi:[0,1]
	v_pk_add_f32 v[130:131], v[130:131], v[138:139] neg_lo:[0,1] neg_hi:[0,1]
	s_waitcnt vmcnt(15)
; __device__ __forceinline__ float bf_lo(unsigned w) { return __uint_as_float(w << 16); }
; __device__ __forceinline__ float bf_hi(unsigned w) { return __uint_as_float(w & 0xffff0000u); }
; __device__ __forceinline__ unsigned pk2(float lo, float hi) { return f2bf(lo) | (f2bf(hi) << 16); }
; template <int W> __device__ __forceinline__ void pool_item(const bfu* u, bfu* pooled, int tb) {
;     ...
;     for (int k = 0; k < 8; ++k) {
;         const v4u c = r[W - 1 + k]; const int t = tb + k;
;         const float cv[8] = {pg8::bf_lo(c.x), pg8::bf_hi(c.x), pg8::bf_lo(c.y), pg8::bf_hi(c.y), pg8::bf_lo(c.z), pg8::bf_hi(c.z), pg8::bf_lo(c.w), pg8::bf_hi(c.w)};
; #pragma unroll
;         for (int e = 0; e < 8; ++e) a[e] += cv[e];
;         const float inv = 1.f / (float)((t + 1) < W ? (t + 1) : W);
;         v4u o; o.x = pk2(a[0] * inv - cv[0], a[1] * inv - cv[1]); o.y = pk2(a[2] * inv - cv[2], a[3] * inv - cv[3]); o.z = pk2(a[4] * inv - cv[4], a[5] * inv - cv[5]); o.w = pk2(a[6] * inv - cv[6], a[7] * inv - cv[7]);
;         *(v4u*)(pooled + (size_t)t * 2048) = o;
;         const v4u d = r[k];
;         a[0] -= pg8::bf_lo(d.x); a[1] -= pg8::bf_hi(d.x); a[2] -= pg8::bf_lo(d.y); a[3] -= pg8::bf_hi(d.y); a[4] -= pg8::bf_lo(d.z); a[5] -= pg8::bf_hi(d.z); a[6] -= pg8::bf_lo(d.w); a[7] -= pg8::bf_hi(d.w);
;     }
	v_lshlrev_b32_e32 v132, 16, v68
	v_and_b32_e32 v133, 0xffff0000, v68
	v_lshlrev_b32_e32 v134, 16, v69
	v_and_b32_e32 v135, 0xffff0000, v69
	v_lshlrev_b32_e32 v136, 16, v70
	v_and_b32_e32 v137, 0xffff0000, v70
	v_lshlrev_b32_e32 v138, 16, v71
	v_and_b32_e32 v139, 0xffff0000, v71
	v_pk_add_f32 v[124:125], v[124:125], v[132:133]
	v_pk_add_f32 v[126:127], v[126:127], v[134:135]
	v_pk_add_f32 v[128:129], v[128:129], v[136:137]
	v_pk_add_f32 v[130:131], v[130:131], v[138:139]
	v_pk_fma_f32 v[132:133], v[148:149], v[124:125], v[132:133] neg_lo:[0,0,1] neg_hi:[0,0,1]
	v_pk_fma_f32 v[134:135], v[148:149], v[126:127], v[134:135] neg_lo:[0,0,1] neg_hi:[0,0,1]
	v_pk_fma_f32 v[136:137], v[148:149], v[128:129], v[136:137] neg_lo:[0,0,1] neg_hi:[0,0,1]
	v_pk_fma_f32 v[138:139], v[148:149], v[130:131], v[138:139] neg_lo:[0,0,1] neg_hi:[0,0,1]
	v_cvt_pk_bf16_f32 v140, v132, v133
	v_cvt_pk_bf16_f32 v141, v134, v135
	v_cvt_pk_bf16_f32 v142, v136, v137
	v_cvt_pk_bf16_f32 v143, v138, v139
	v_lshl_add_u64 v[150:151], v[224:225], 0, s[70:71]
	s_add_u32 s70, s70, 0x1000
	global_store_dwordx4 v[150:151], v[140:143], off
	v_cndmask_b32_e64 v144, v40, v8, s[68:69]
	v_cndmask_b32_e64 v145, v41, v9, s[68:69]
	v_cndmask_b32_e64 v146, v42, v10, s[68:69]
	v_cndmask_b32_e64 v147, v43, v11, s[68:69]
	v_lshlrev_b32_e32 v132, 16, v144
	v_and_b32_e32 v133, 0xffff0000, v144
	v_lshlrev_b32_e32 v134, 16, v145
	v_and_b32_e32 v135, 0xffff0000, v145
	v_lshlrev_b32_e32 v136, 16, v146
	v_and_b32_e32 v137, 0xffff0000, v146
	v_lshlrev_b32_e32 v138, 16, v147
	v_and_b32_e32 v139, 0xffff0000, v147
	v_pk_add_f32 v[124:125], v[124:125], v[132:133] neg_lo:[0,1] neg_hi:[0,1]
	v_pk_add_f32 v[126:127], v[126:127], v[134:135] neg_lo:[0,1] neg_hi:[0,1]
	v_pk_add_f32 v[128:129], v[128:129], v[136:137] neg_lo:[0,1] neg_hi:[0,1]
	v_pk_add_f32 v[130:131], v[130:131], v[138:139] neg_lo:[0,1] neg_hi:[0,1]
	s_waitcnt vmcnt(15)
	v_lshlrev_b32_e32 v132, 16, v72
	v_and_b32_e32 v133, 0xffff0000, v72
	v_lshlrev_b32_e32 v134, 16, v73
	v_and_b32_e32 v135, 0xffff0000, v73
	v_lshlrev_b32_e32 v136, 16, v74
	v_and_b32_e32 v137, 0xffff0000, v74
	v_lshlrev_b32_e32 v138, 16, v75
	v_and_b32_e32 v139, 0xffff0000, v75
	v_pk_add_f32 v[124:125], v[124:125], v[132:133]
	v_pk_add_f32 v[126:127], v[126:127], v[134:135]
	v_pk_add_f32 v[128:129], v[128:129], v[136:137]
	v_pk_add_f32 v[130:131], v[130:131], v[138:139]
	v_pk_fma_f32 v[132:133], v[148:149], v[124:125], v[132:133] neg_lo:[0,0,1] neg_hi:[0,0,1]
	v_pk_fma_f32 v[134:135], v[148:149], v[126:127], v[134:135] neg_lo:[0,0,1] neg_hi:[0,0,1]
	v_pk_fma_f32 v[136:137], v[148:149], v[128:129], v[136:137] neg_lo:[0,0,1] neg_hi:[0,0,1]
	v_pk_fma_f32 v[138:139], v[148:149], v[130:131], v[138:139] neg_lo:[0,0,1] neg_hi:[0,0,1]
	v_cvt_pk_bf16_f32 v140, v132, v133
	v_cvt_pk_bf16_f32 v141, v134, v135
	v_cvt_pk_bf16_f32 v142, v136, v137
	v_cvt_pk_bf16_f32 v143, v138, v139
	v_lshl_add_u64 v[150:151], v[224:225], 0, s[70:71]
	s_add_u32 s70, s70, 0x1000
	global_store_dwordx4 v[150:151], v[140:143], off
	v_cndmask_b32_e64 v144, v44, v12, s[68:69]
	v_cndmask_b32_e64 v145, v45, v13, s[68:69]
	v_cndmask_b32_e64 v146, v46, v14, s[68:69]
	v_cndmask_b32_e64 v147, v47, v15, s[68:69]
	v_lshlrev_b32_e32 v132, 16, v144
	v_and_b32_e32 v133, 0xffff0000, v144
	v_lshlrev_b32_e32 v134, 16, v145
	v_and_b32_e32 v135, 0xffff0000, v145
	v_lshlrev_b32_e32 v136, 16, v146
	v_and_b32_e32 v137, 0xffff0000, v146
	v_lshlrev_b32_e32 v138, 16, v147
	v_and_b32_e32 v139, 0xffff0000, v147
	v_pk_add_f32 v[124:125], v[124:125], v[132:133] neg_lo:[0,1] neg_hi:[0,1]
	v_pk_add_f32 v[126:127], v[126:127], v[134:135] neg_lo:[0,1] neg_hi:[0,1]
	v_pk_add_f32 v[128:129], v[128:129], v[136:137] neg_lo:[0,1] neg_hi:[0,1]
	v_pk_add_f32 v[130:131], v[130:131], v[138:139] neg_lo:[0,1] neg_hi:[0,1]
	s_waitcnt vmcnt(15)
	v_lshlrev_b32_e32 v132, 16, v76
	v_and_b32_e32 v133, 0xffff0000, v76
	v_lshlrev_b32_e32 v134, 16, v77
	v_and_b32_e32 v135, 0xffff0000, v77
	v_lshlrev_b32_e32 v136, 16, v78
	v_and_b32_e32 v137, 0xffff0000, v78
	v_lshlrev_b32_e32 v138, 16, v79
	v_and_b32_e32 v139, 0xffff0000, v79
	v_pk_add_f32 v[124:125], v[124:125], v[132:133]
	v_pk_add_f32 v[126:127], v[126:127], v[134:135]
	v_pk_add_f32 v[128:129], v[128:129], v[136:137]
	v_pk_add_f32 v[130:131], v[130:131], v[138:139]
	v_pk_fma_f32 v[132:133], v[148:149], v[124:125], v[132:133] neg_lo:[0,0,1] neg_hi:[0,0,1]
	v_pk_fma_f32 v[134:135], v[148:149], v[126:127], v[134:135] neg_lo:[0,0,1] neg_hi:[0,0,1]
	v_pk_fma_f32 v[136:137], v[148:149], v[128:129], v[136:137] neg_lo:[0,0,1] neg_hi:[0,0,1]
	v_pk_fma_f32 v[138:139], v[148:149], v[130:131], v[138:139] neg_lo:[0,0,1] neg_hi:[0,0,1]
	v_cvt_pk_bf16_f32 v140, v132, v133
	v_cvt_pk_bf16_f32 v141, v134, v135
	v_cvt_pk_bf16_f32 v142, v136, v137
	v_cvt_pk_bf16_f32 v143, v138, v139
	v_lshl_add_u64 v[150:151], v[224:225], 0, s[70:71]
	s_add_u32 s70, s70, 0x1000
	global_store_dwordx4 v[150:151], v[140:143], off
	v_cndmask_b32_e64 v144, v48, v16, s[68:69]
	v_cndmask_b32_e64 v145, v49, v17, s[68:69]
	v_cndmask_b32_e64 v146, v50, v18, s[68:69]
	v_cndmask_b32_e64 v147, v51, v19, s[68:69]
	v_lshlrev_b32_e32 v132, 16, v144
	v_and_b32_e32 v133, 0xffff0000, v144
	v_lshlrev_b32_e32 v134, 16, v145
	v_and_b32_e32 v135, 0xffff0000, v145
	v_lshlrev_b32_e32 v136, 16, v146
	v_and_b32_e32 v137, 0xffff0000, v146
	v_lshlrev_b32_e32 v138, 16, v147
	v_and_b32_e32 v139, 0xffff0000, v147
	v_pk_add_f32 v[124:125], v[124:125], v[132:133] neg_lo:[0,1] neg_hi:[0,1]
	v_pk_add_f32 v[126:127], v[126:127], v[134:135] neg_lo:[0,1] neg_hi:[0,1]
	v_pk_add_f32 v[128:129], v[128:129], v[136:137] neg_lo:[0,1] neg_hi:[0,1]
	v_pk_add_f32 v[130:131], v[130:131], v[138:139] neg_lo:[0,1] neg_hi:[0,1]
	s_waitcnt vmcnt(15)
; __device__ __forceinline__ float bf_lo(unsigned w) { return __uint_as_float(w << 16); }
; __device__ __forceinline__ float bf_hi(unsigned w) { return __uint_as_float(w & 0xffff0000u); }
; __device__ __forceinline__ unsigned pk2(float lo, float hi) { return f2bf(lo) | (f2bf(hi) << 16); }
; template <int W> __device__ __forceinline__ void pool_item(const bfu* u, bfu* pooled, int tb) {
;     ...
;     for (int k = 0; k < 8; ++k) {
;         const v4u c = r[W - 1 + k]; const int t = tb + k;
;         const float cv[8] = {pg8::bf_lo(c.x), pg8::bf_hi(c.x), pg8::bf_lo(c.y), pg8::bf_hi(c.y), pg8::bf_lo(c.z), pg8::bf_hi(c.z), pg8::bf_lo(c.w), pg8::bf_hi(c.w)};
; #pragma unroll
;         for (int e = 0; e < 8; ++e) a[e] += cv[e];
;         const float inv = 1.f / (float)((t + 1) < W ? (t + 1) : W);
;         v4u o; o.x = pk2(a[0] * inv - cv[0], a[1] * inv - cv[1]); o.y = pk2(a[2] * inv - cv[2], a[3] * inv - cv[3]); o.z = pk2(a[4] * inv - cv[4], a[5] * inv - cv[5]); o.w = pk2(a[6] * inv - cv[6], a[7] * inv - cv[7]);
;         *(v4u*)(pooled + (size_t)t * 2048) = o;
;         const v4u d = r[k];
;         a[0] -= pg8::bf_lo(d.x); a[1] -= pg8::bf_hi(d.x); a[2] -= pg8::bf_lo(d.y); a[3] -= pg8::bf_hi(d.y); a[4] -= pg8::bf_lo(d.z); a[5] -= pg8::bf_hi(d.z); a[6] -= pg8::bf_lo(d.w); a[7] -= pg8::bf_hi(d.w);
;     }
	v_lshlrev_b32_e32 v132, 16, v80
	v_and_b32_e32 v133, 0xffff0000, v80
	v_lshlrev_b32_e32 v134, 16, v81
	v_and_b32_e32 v135, 0xffff0000, v81
	v_lshlrev_b32_e32 v136, 16, v82
	v_and_b32_e32 v137, 0xffff0000, v82
	v_lshlrev_b32_e32 v138, 16, v83
	v_and_b32_e32 v139, 0xffff0000, v83
	v_pk_add_f32 v[124:125], v[124:125], v[132:133]
	v_pk_add_f32 v[126:127], v[126:127], v[134:135]
	v_pk_add_f32 v[128:129], v[128:129], v[136:137]
	v_pk_add_f32 v[130:131], v[130:131], v[138:139]
	v_pk_fma_f32 v[132:133], v[148:149], v[124:125], v[132:133] neg_lo:[0,0,1] neg_hi:[0,0,1]
	v_pk_fma_f32 v[134:135], v[148:149], v[126:127], v[134:135] neg_lo:[0,0,1] neg_hi:[0,0,1]
	v_pk_fma_f32 v[136:137], v[148:149], v[128:129], v[136:137] neg_lo:[0,0,1] neg_hi:[0,0,1]
	v_pk_fma_f32 v[138:139], v[148:149], v[130:131], v[138:139] neg_lo:[0,0,1] neg_hi:[0,0,1]
	v_cvt_pk_bf16_f32 v140, v132, v133
	v_cvt_pk_bf16_f32 v141, v134, v135
	v_cvt_pk_bf16_f32 v142, v136, v137
	v_cvt_pk_bf16_f32 v143, v138, v139
	v_lshl_add_u64 v[150:151], v[224:225], 0, s[70:71]
	s_add_u32 s70, s70, 0x1000
	global_store_dwordx4 v[150:151], v[140:143], off
	v_cndmask_b32_e64 v144, v52, v20, s[68:69]
	v_cndmask_b32_e64 v145, v53, v21, s[68:69]
	v_cndmask_b32_e64 v146, v54, v22, s[68:69]
	v_cndmask_b32_e64 v147, v55, v23, s[68:69]
	v_lshlrev_b32_e32 v132, 16, v144
	v_and_b32_e32 v133, 0xffff0000, v144
	v_lshlrev_b32_e32 v134, 16, v145
	v_and_b32_e32 v135, 0xffff0000, v145
	v_lshlrev_b32_e32 v136, 16, v146
	v_and_b32_e32 v137, 0xffff0000, v146
	v_lshlrev_b32_e32 v138, 16, v147
	v_and_b32_e32 v139, 0xffff0000, v147
	v_pk_add_f32 v[124:125], v[124:125], v[132:133] neg_lo:[0,1] neg_hi:[0,1]
	v_pk_add_f32 v[126:127], v[126:127], v[134:135] neg_lo:[0,1] neg_hi:[0,1]
	v_pk_add_f32 v[128:129], v[128:129], v[136:137] neg_lo:[0,1] neg_hi:[0,1]
	v_pk_add_f32 v[130:131], v[130:131], v[138:139] neg_lo:[0,1] neg_hi:[0,1]
	s_waitcnt vmcnt(15)
	v_lshlrev_b32_e32 v132, 16, v84
	v_and_b32_e32 v133, 0xffff0000, v84
	v_lshlrev_b32_e32 v134, 16, v85
	v_and_b32_e32 v135, 0xffff0000, v85
	v_lshlrev_b32_e32 v136, 16, v86
	v_and_b32_e32 v137, 0xffff0000, v86
	v_lshlrev_b32_e32 v138, 16, v87
	v_and_b32_e32 v139, 0xffff0000, v87
	v_pk_add_f32 v[124:125], v[124:125], v[132:133]
	v_pk_add_f32 v[126:127], v[126:127], v[134:135]
	v_pk_add_f32 v[128:129], v[128:129], v[136:137]
	v_pk_add_f32 v[130:131], v[130:131], v[138:139]
	v_pk_fma_f32 v[132:133], v[148:149], v[124:125], v[132:133] neg_lo:[0,0,1] neg_hi:[0,0,1]
	v_pk_fma_f32 v[134:135], v[148:149], v[126:127], v[134:135] neg_lo:[0,0,1] neg_hi:[0,0,1]
	v_pk_fma_f32 v[136:137], v[148:149], v[128:129], v[136:137] neg_lo:[0,0,1] neg_hi:[0,0,1]
	v_pk_fma_f32 v[138:139], v[148:149], v[130:131], v[138:139] neg_lo:[0,0,1] neg_hi:[0,0,1]
	v_cvt_pk_bf16_f32 v140, v132, v133
	v_cvt_pk_bf16_f32 v141, v134, v135
	v_cvt_pk_bf16_f32 v142, v136, v137
	v_cvt_pk_bf16_f32 v143, v138, v139
	v_lshl_add_u64 v[150:151], v[224:225], 0, s[70:71]
	s_add_u32 s70, s70, 0x1000
	global_store_dwordx4 v[150:151], v[140:143], off
	v_cndmask_b32_e64 v144, v56, v24, s[68:69]
	v_cndmask_b32_e64 v145, v57, v25, s[68:69]
	v_cndmask_b32_e64 v146, v58, v26, s[68:69]
	v_cndmask_b32_e64 v147, v59, v27, s[68:69]
	v_lshlrev_b32_e32 v132, 16, v144
	v_and_b32_e32 v133, 0xffff0000, v144
	v_lshlrev_b32_e32 v134, 16, v145
	v_and_b32_e32 v135, 0xffff0000, v145
	v_lshlrev_b32_e32 v136, 16, v146
	v_and_b32_e32 v137, 0xffff0000, v146
	v_lshlrev_b32_e32 v138, 16, v147
	v_and_b32_e32 v139, 0xffff0000, v147
	v_pk_add_f32 v[124:125], v[124:125], v[132:133] neg_lo:[0,1] neg_hi:[0,1]
	v_pk_add_f32 v[126:127], v[126:127], v[134:135] neg_lo:[0,1] neg_hi:[0,1]
	v_pk_add_f32 v[128:129], v[128:129], v[136:137] neg_lo:[0,1] neg_hi:[0,1]
	v_pk_add_f32 v[130:131], v[130:131], v[138:139] neg_lo:[0,1] neg_hi:[0,1]
	s_waitcnt vmcnt(15)
	v_lshlrev_b32_e32 v132, 16, v88
	v_and_b32_e32 v133, 0xffff0000, v88
	v_lshlrev_b32_e32 v134, 16, v89
	v_and_b32_e32 v135, 0xffff0000, v89
	v_lshlrev_b32_e32 v136, 16, v90
	v_and_b32_e32 v137, 0xffff0000, v90
	v_lshlrev_b32_e32 v138, 16, v91
	v_and_b32_e32 v139, 0xffff0000, v91
	v_pk_add_f32 v[124:125], v[124:125], v[132:133]
	v_pk_add_f32 v[126:127], v[126:127], v[134:135]
	v_pk_add_f32 v[128:129], v[128:129], v[136:137]
	v_pk_add_f32 v[130:131], v[130:131], v[138:139]
	v_pk_fma_f32 v[132:133], v[148:149], v[124:125], v[132:133] neg_lo:[0,0,1] neg_hi:[0,0,1]
	v_pk_fma_f32 v[134:135], v[148:149], v[126:127], v[134:135] neg_lo:[0,0,1] neg_hi:[0,0,1]
	v_pk_fma_f32 v[136:137], v[148:149], v[128:129], v[136:137] neg_lo:[0,0,1] neg_hi:[0,0,1]
	v_pk_fma_f32 v[138:139], v[148:149], v[130:131], v[138:139] neg_lo:[0,0,1] neg_hi:[0,0,1]
	v_cvt_pk_bf16_f32 v140, v132, v133
	v_cvt_pk_bf16_f32 v141, v134, v135
	v_cvt_pk_bf16_f32 v142, v136, v137
	v_cvt_pk_bf16_f32 v143, v138, v139
	v_lshl_add_u64 v[150:151], v[224:225], 0, s[70:71]
	s_add_u32 s70, s70, 0x1000
	global_store_dwordx4 v[150:151], v[140:143], off
	v_cndmask_b32_e64 v144, v60, v28, s[68:69]
	v_cndmask_b32_e64 v145, v61, v29, s[68:69]
	v_cndmask_b32_e64 v146, v62, v30, s[68:69]
	v_cndmask_b32_e64 v147, v63, v31, s[68:69]
	v_lshlrev_b32_e32 v132, 16, v144
	v_and_b32_e32 v133, 0xffff0000, v144
	v_lshlrev_b32_e32 v134, 16, v145
	v_and_b32_e32 v135, 0xffff0000, v145
	v_lshlrev_b32_e32 v136, 16, v146
	v_and_b32_e32 v137, 0xffff0000, v146
	v_lshlrev_b32_e32 v138, 16, v147
	v_and_b32_e32 v139, 0xffff0000, v147
	v_pk_add_f32 v[124:125], v[124:125], v[132:133] neg_lo:[0,1] neg_hi:[0,1]
	v_pk_add_f32 v[126:127], v[126:127], v[134:135] neg_lo:[0,1] neg_hi:[0,1]
	v_pk_add_f32 v[128:129], v[128:129], v[136:137] neg_lo:[0,1] neg_hi:[0,1]
	v_pk_add_f32 v[130:131], v[130:131], v[138:139] neg_lo:[0,1] neg_hi:[0,1]
	s_waitcnt vmcnt(15)
; __device__ __forceinline__ float bf_lo(unsigned w) { return __uint_as_float(w << 16); }
; __device__ __forceinline__ float bf_hi(unsigned w) { return __uint_as_float(w & 0xffff0000u); }
; __device__ __forceinline__ unsigned pk2(float lo, float hi) { return f2bf(lo) | (f2bf(hi) << 16); }
; template <int W> __device__ __forceinline__ void pool_item(const bfu* u, bfu* pooled, int tb) {
;     ...
;     for (int k = 0; k < 8; ++k) {
;         const v4u c = r[W - 1 + k]; const int t = tb + k;
;         const float cv[8] = {pg8::bf_lo(c.x), pg8::bf_hi(c.x), pg8::bf_lo(c.y), pg8::bf_hi(c.y), pg8::bf_lo(c.z), pg8::bf_hi(c.z), pg8::bf_lo(c.w), pg8::bf_hi(c.w)};
; #pragma unroll
;         for (int e = 0; e < 8; ++e) a[e] += cv[e];
;         const float inv = 1.f / (float)((t + 1) < W ? (t + 1) : W);
;         v4u o; o.x = pk2(a[0] * inv - cv[0], a[1] * inv - cv[1]); o.y = pk2(a[2] * inv - cv[2], a[3] * inv - cv[3]); o.z = pk2(a[4] * inv - cv[4], a[5] * inv - cv[5]); o.w = pk2(a[6] * inv - cv[6], a[7] * inv - cv[7]);
;         *(v4u*)(pooled + (size_t)t * 2048) = o;
;         const v4u d = r[k];
;         a[0] -= pg8::bf_lo(d.x); a[1] -= pg8::bf_hi(d.x); a[2] -= pg8::bf_lo(d.y); a[3] -= pg8::bf_hi(d.y); a[4] -= pg8::bf_lo(d.z); a[5] -= pg8::bf_hi(d.z); a[6] -= pg8::bf_lo(d.w); a[7] -= pg8::bf_hi(d.w);
;     }
	v_lshlrev_b32_e32 v132, 16, v92
	v_and_b32_e32 v133, 0xffff0000, v92
	v_lshlrev_b32_e32 v134, 16, v93
	v_and_b32_e32 v135, 0xffff0000, v93
	v_lshlrev_b32_e32 v136, 16, v94
	v_and_b32_e32 v137, 0xffff0000, v94
	v_lshlrev_b32_e32 v138, 16, v95
	v_and_b32_e32 v139, 0xffff0000, v95
	v_pk_add_f32 v[124:125], v[124:125], v[132:133]
	v_pk_add_f32 v[126:127], v[126:127], v[134:135]
	v_pk_add_f32 v[128:129], v[128:129], v[136:137]
	v_pk_add_f32 v[130:131], v[130:131], v[138:139]
	v_pk_fma_f32 v[132:133], v[148:149], v[124:125], v[132:133] neg_lo:[0,0,1] neg_hi:[0,0,1]
	v_pk_fma_f32 v[134:135], v[148:149], v[126:127], v[134:135] neg_lo:[0,0,1] neg_hi:[0,0,1]
	v_pk_fma_f32 v[136:137], v[148:149], v[128:129], v[136:137] neg_lo:[0,0,1] neg_hi:[0,0,1]
	v_pk_fma_f32 v[138:139], v[148:149], v[130:131], v[138:139] neg_lo:[0,0,1] neg_hi:[0,0,1]
	v_cvt_pk_bf16_f32 v140, v132, v133
	v_cvt_pk_bf16_f32 v141, v134, v135
	v_cvt_pk_bf16_f32 v142, v136, v137
	v_cvt_pk_bf16_f32 v143, v138, v139
	v_lshl_add_u64 v[150:151], v[224:225], 0, s[70:71]
	s_add_u32 s70, s70, 0x1000
	global_store_dwordx4 v[150:151], v[140:143], off
	v_cndmask_b32_e64 v144, v64, v32, s[68:69]
	v_cndmask_b32_e64 v145, v65, v33, s[68:69]
	v_cndmask_b32_e64 v146, v66, v34, s[68:69]
	v_cndmask_b32_e64 v147, v67, v35, s[68:69]
	v_lshlrev_b32_e32 v132, 16, v144
	v_and_b32_e32 v133, 0xffff0000, v144
	v_lshlrev_b32_e32 v134, 16, v145
	v_and_b32_e32 v135, 0xffff0000, v145
	v_lshlrev_b32_e32 v136, 16, v146
	v_and_b32_e32 v137, 0xffff0000, v146
	v_lshlrev_b32_e32 v138, 16, v147
	v_and_b32_e32 v139, 0xffff0000, v147
	v_pk_add_f32 v[124:125], v[124:125], v[132:133] neg_lo:[0,1] neg_hi:[0,1]
	v_pk_add_f32 v[126:127], v[126:127], v[134:135] neg_lo:[0,1] neg_hi:[0,1]
	v_pk_add_f32 v[128:129], v[128:129], v[136:137] neg_lo:[0,1] neg_hi:[0,1]
	v_pk_add_f32 v[130:131], v[130:131], v[138:139] neg_lo:[0,1] neg_hi:[0,1]
	s_waitcnt vmcnt(15)
	v_lshlrev_b32_e32 v132, 16, v96
	v_and_b32_e32 v133, 0xffff0000, v96
	v_lshlrev_b32_e32 v134, 16, v97
	v_and_b32_e32 v135, 0xffff0000, v97
	v_lshlrev_b32_e32 v136, 16, v98
	v_and_b32_e32 v137, 0xffff0000, v98
	v_lshlrev_b32_e32 v138, 16, v99
	v_and_b32_e32 v139, 0xffff0000, v99
	v_pk_add_f32 v[124:125], v[124:125], v[132:133]
	v_pk_add_f32 v[126:127], v[126:127], v[134:135]
	v_pk_add_f32 v[128:129], v[128:129], v[136:137]
	v_pk_add_f32 v[130:131], v[130:131], v[138:139]
	v_pk_fma_f32 v[132:133], v[148:149], v[124:125], v[132:133] neg_lo:[0,0,1] neg_hi:[0,0,1]
	v_pk_fma_f32 v[134:135], v[148:149], v[126:127], v[134:135] neg_lo:[0,0,1] neg_hi:[0,0,1]
	v_pk_fma_f32 v[136:137], v[148:149], v[128:129], v[136:137] neg_lo:[0,0,1] neg_hi:[0,0,1]
	v_pk_fma_f32 v[138:139], v[148:149], v[130:131], v[138:139] neg_lo:[0,0,1] neg_hi:[0,0,1]
	v_cvt_pk_bf16_f32 v140, v132, v133
	v_cvt_pk_bf16_f32 v141, v134, v135
	v_cvt_pk_bf16_f32 v142, v136, v137
	v_cvt_pk_bf16_f32 v143, v138, v139
	v_lshl_add_u64 v[150:151], v[224:225], 0, s[70:71]
	s_add_u32 s70, s70, 0x1000
	global_store_dwordx4 v[150:151], v[140:143], off
	v_cndmask_b32_e64 v144, v68, v36, s[68:69]
	v_cndmask_b32_e64 v145, v69, v37, s[68:69]
	v_cndmask_b32_e64 v146, v70, v38, s[68:69]
	v_cndmask_b32_e64 v147, v71, v39, s[68:69]
	v_lshlrev_b32_e32 v132, 16, v144
	v_and_b32_e32 v133, 0xffff0000, v144
	v_lshlrev_b32_e32 v134, 16, v145
	v_and_b32_e32 v135, 0xffff0000, v145
	v_lshlrev_b32_e32 v136, 16, v146
	v_and_b32_e32 v137, 0xffff0000, v146
	v_lshlrev_b32_e32 v138, 16, v147
	v_and_b32_e32 v139, 0xffff0000, v147
	v_pk_add_f32 v[124:125], v[124:125], v[132:133] neg_lo:[0,1] neg_hi:[0,1]
	v_pk_add_f32 v[126:127], v[126:127], v[134:135] neg_lo:[0,1] neg_hi:[0,1]
	v_pk_add_f32 v[128:129], v[128:129], v[136:137] neg_lo:[0,1] neg_hi:[0,1]
	v_pk_add_f32 v[130:131], v[130:131], v[138:139] neg_lo:[0,1] neg_hi:[0,1]
	s_waitcnt vmcnt(15)
	v_lshlrev_b32_e32 v132, 16, v100
	v_and_b32_e32 v133, 0xffff0000, v100
	v_lshlrev_b32_e32 v134, 16, v101
	v_and_b32_e32 v135, 0xffff0000, v101
	v_lshlrev_b32_e32 v136, 16, v102
	v_and_b32_e32 v137, 0xffff0000, v102
	v_lshlrev_b32_e32 v138, 16, v103
	v_and_b32_e32 v139, 0xffff0000, v103
	v_pk_add_f32 v[124:125], v[124:125], v[132:133]
	v_pk_add_f32 v[126:127], v[126:127], v[134:135]
	v_pk_add_f32 v[128:129], v[128:129], v[136:137]
	v_pk_add_f32 v[130:131], v[130:131], v[138:139]
	v_pk_fma_f32 v[132:133], v[148:149], v[124:125], v[132:133] neg_lo:[0,0,1] neg_hi:[0,0,1]
	v_pk_fma_f32 v[134:135], v[148:149], v[126:127], v[134:135] neg_lo:[0,0,1] neg_hi:[0,0,1]
	v_pk_fma_f32 v[136:137], v[148:149], v[128:129], v[136:137] neg_lo:[0,0,1] neg_hi:[0,0,1]
	v_pk_fma_f32 v[138:139], v[148:149], v[130:131], v[138:139] neg_lo:[0,0,1] neg_hi:[0,0,1]
	v_cvt_pk_bf16_f32 v140, v132, v133
	v_cvt_pk_bf16_f32 v141, v134, v135
	v_cvt_pk_bf16_f32 v142, v136, v137
	v_cvt_pk_bf16_f32 v143, v138, v139
	v_lshl_add_u64 v[150:151], v[224:225], 0, s[70:71]
	s_add_u32 s70, s70, 0x1000
	global_store_dwordx4 v[150:151], v[140:143], off
	v_cndmask_b32_e64 v144, v72, v40, s[68:69]
	v_cndmask_b32_e64 v145, v73, v41, s[68:69]
	v_cndmask_b32_e64 v146, v74, v42, s[68:69]
	v_cndmask_b32_e64 v147, v75, v43, s[68:69]
	v_lshlrev_b32_e32 v132, 16, v144
	v_and_b32_e32 v133, 0xffff0000, v144
	v_lshlrev_b32_e32 v134, 16, v145
	v_and_b32_e32 v135, 0xffff0000, v145
	v_lshlrev_b32_e32 v136, 16, v146
	v_and_b32_e32 v137, 0xffff0000, v146
	v_lshlrev_b32_e32 v138, 16, v147
	v_and_b32_e32 v139, 0xffff0000, v147
	v_pk_add_f32 v[124:125], v[124:125], v[132:133] neg_lo:[0,1] neg_hi:[0,1]
	v_pk_add_f32 v[126:127], v[126:127], v[134:135] neg_lo:[0,1] neg_hi:[0,1]
	v_pk_add_f32 v[128:129], v[128:129], v[136:137] neg_lo:[0,1] neg_hi:[0,1]
	v_pk_add_f32 v[130:131], v[130:131], v[138:139] neg_lo:[0,1] neg_hi:[0,1]
	s_waitcnt vmcnt(15)
; __device__ __forceinline__ float bf_lo(unsigned w) { return __uint_as_float(w << 16); }
; __device__ __forceinline__ float bf_hi(unsigned w) { return __uint_as_float(w & 0xffff0000u); }
; __device__ __forceinline__ unsigned pk2(float lo, float hi) { return f2bf(lo) | (f2bf(hi) << 16); }
; template <int W> __device__ __forceinline__ void pool_item(const bfu* u, bfu* pooled, int tb) {
;     ...
;     for (int k = 0; k < 8; ++k) {
;         const v4u c = r[W - 1 + k]; const int t = tb + k;
;         const float cv[8] = {pg8::bf_lo(c.x), pg8::bf_hi(c.x), pg8::bf_lo(c.y), pg8::bf_hi(c.y), pg8::bf_lo(c.z), pg8::bf_hi(c.z), pg8::bf_lo(c.w), pg8::bf_hi(c.w)};
; #pragma unroll
;         for (int e = 0; e < 8; ++e) a[e] += cv[e];
;         const float inv = 1.f / (float)((t + 1) < W ? (t + 1) : W);
;         v4u o; o.x = pk2(a[0] * inv - cv[0], a[1] * inv - cv[1]); o.y = pk2(a[2] * inv - cv[2], a[3] * inv - cv[3]); o.z = pk2(a[4] * inv - cv[4], a[5] * inv - cv[5]); o.w = pk2(a[6] * inv - cv[6], a[7] * inv - cv[7]);
;         *(v4u*)(pooled + (size_t)t * 2048) = o;
;         const v4u d = r[k];
;         a[0] -= pg8::bf_lo(d.x); a[1] -= pg8::bf_hi(d.x); a[2] -= pg8::bf_lo(d.y); a[3] -= pg8::bf_hi(d.y); a[4] -= pg8::bf_lo(d.z); a[5] -= pg8::bf_hi(d.z); a[6] -= pg8::bf_lo(d.w); a[7] -= pg8::bf_hi(d.w);
;     }
	v_lshlrev_b32_e32 v132, 16, v104
	v_and_b32_e32 v133, 0xffff0000, v104
	v_lshlrev_b32_e32 v134, 16, v105
	v_and_b32_e32 v135, 0xffff0000, v105
	v_lshlrev_b32_e32 v136, 16, v106
	v_and_b32_e32 v137, 0xffff0000, v106
	v_lshlrev_b32_e32 v138, 16, v107
	v_and_b32_e32 v139, 0xffff0000, v107
	v_pk_add_f32 v[124:125], v[124:125], v[132:133]
	v_pk_add_f32 v[126:127], v[126:127], v[134:135]
	v_pk_add_f32 v[128:129], v[128:129], v[136:137]
	v_pk_add_f32 v[130:131], v[130:131], v[138:139]
	v_pk_fma_f32 v[132:133], v[148:149], v[124:125], v[132:133] neg_lo:[0,0,1] neg_hi:[0,0,1]
	v_pk_fma_f32 v[134:135], v[148:149], v[126:127], v[134:135] neg_lo:[0,0,1] neg_hi:[0,0,1]
	v_pk_fma_f32 v[136:137], v[148:149], v[128:129], v[136:137] neg_lo:[0,0,1] neg_hi:[0,0,1]
	v_pk_fma_f32 v[138:139], v[148:149], v[130:131], v[138:139] neg_lo:[0,0,1] neg_hi:[0,0,1]
	v_cvt_pk_bf16_f32 v140, v132, v133
	v_cvt_pk_bf16_f32 v141, v134, v135
	v_cvt_pk_bf16_f32 v142, v136, v137
	v_cvt_pk_bf16_f32 v143, v138, v139
	v_lshl_add_u64 v[150:151], v[224:225], 0, s[70:71]
	s_add_u32 s70, s70, 0x1000
	global_store_dwordx4 v[150:151], v[140:143], off
	v_cndmask_b32_e64 v144, v76, v44, s[68:69]
	v_cndmask_b32_e64 v145, v77, v45, s[68:69]
	v_cndmask_b32_e64 v146, v78, v46, s[68:69]
	v_cndmask_b32_e64 v147, v79, v47, s[68:69]
	v_lshlrev_b32_e32 v132, 16, v144
	v_and_b32_e32 v133, 0xffff0000, v144
	v_lshlrev_b32_e32 v134, 16, v145
	v_and_b32_e32 v135, 0xffff0000, v145
	v_lshlrev_b32_e32 v136, 16, v146
	v_and_b32_e32 v137, 0xffff0000, v146
	v_lshlrev_b32_e32 v138, 16, v147
	v_and_b32_e32 v139, 0xffff0000, v147
	v_pk_add_f32 v[124:125], v[124:125], v[132:133] neg_lo:[0,1] neg_hi:[0,1]
	v_pk_add_f32 v[126:127], v[126:127], v[134:135] neg_lo:[0,1] neg_hi:[0,1]
	v_pk_add_f32 v[128:129], v[128:129], v[136:137] neg_lo:[0,1] neg_hi:[0,1]
	v_pk_add_f32 v[130:131], v[130:131], v[138:139] neg_lo:[0,1] neg_hi:[0,1]
	s_waitcnt vmcnt(15)
	v_lshlrev_b32_e32 v132, 16, v108
	v_and_b32_e32 v133, 0xffff0000, v108
	v_lshlrev_b32_e32 v134, 16, v109
	v_and_b32_e32 v135, 0xffff0000, v109
	v_lshlrev_b32_e32 v136, 16, v110
	v_and_b32_e32 v137, 0xffff0000, v110
	v_lshlrev_b32_e32 v138, 16, v111
	v_and_b32_e32 v139, 0xffff0000, v111
	v_pk_add_f32 v[124:125], v[124:125], v[132:133]
	v_pk_add_f32 v[126:127], v[126:127], v[134:135]
	v_pk_add_f32 v[128:129], v[128:129], v[136:137]
	v_pk_add_f32 v[130:131], v[130:131], v[138:139]
	v_pk_fma_f32 v[132:133], v[148:149], v[124:125], v[132:133] neg_lo:[0,0,1] neg_hi:[0,0,1]
	v_pk_fma_f32 v[134:135], v[148:149], v[126:127], v[134:135] neg_lo:[0,0,1] neg_hi:[0,0,1]
	v_pk_fma_f32 v[136:137], v[148:149], v[128:129], v[136:137] neg_lo:[0,0,1] neg_hi:[0,0,1]
	v_pk_fma_f32 v[138:139], v[148:149], v[130:131], v[138:139] neg_lo:[0,0,1] neg_hi:[0,0,1]
	v_cvt_pk_bf16_f32 v140, v132, v133
	v_cvt_pk_bf16_f32 v141, v134, v135
	v_cvt_pk_bf16_f32 v142, v136, v137
	v_cvt_pk_bf16_f32 v143, v138, v139
	v_lshl_add_u64 v[150:151], v[224:225], 0, s[70:71]
	s_add_u32 s70, s70, 0x1000
	global_store_dwordx4 v[150:151], v[140:143], off
	v_cndmask_b32_e64 v144, v80, v48, s[68:69]
	v_cndmask_b32_e64 v145, v81, v49, s[68:69]
	v_cndmask_b32_e64 v146, v82, v50, s[68:69]
	v_cndmask_b32_e64 v147, v83, v51, s[68:69]
	v_lshlrev_b32_e32 v132, 16, v144
	v_and_b32_e32 v133, 0xffff0000, v144
	v_lshlrev_b32_e32 v134, 16, v145
	v_and_b32_e32 v135, 0xffff0000, v145
	v_lshlrev_b32_e32 v136, 16, v146
	v_and_b32_e32 v137, 0xffff0000, v146
	v_lshlrev_b32_e32 v138, 16, v147
	v_and_b32_e32 v139, 0xffff0000, v147
	v_pk_add_f32 v[124:125], v[124:125], v[132:133] neg_lo:[0,1] neg_hi:[0,1]
	v_pk_add_f32 v[126:127], v[126:127], v[134:135] neg_lo:[0,1] neg_hi:[0,1]
	v_pk_add_f32 v[128:129], v[128:129], v[136:137] neg_lo:[0,1] neg_hi:[0,1]
	v_pk_add_f32 v[130:131], v[130:131], v[138:139] neg_lo:[0,1] neg_hi:[0,1]
	s_waitcnt vmcnt(15)
	v_lshlrev_b32_e32 v132, 16, v112
	v_and_b32_e32 v133, 0xffff0000, v112
	v_lshlrev_b32_e32 v134, 16, v113
	v_and_b32_e32 v135, 0xffff0000, v113
	v_lshlrev_b32_e32 v136, 16, v114
	v_and_b32_e32 v137, 0xffff0000, v114
	v_lshlrev_b32_e32 v138, 16, v115
	v_and_b32_e32 v139, 0xffff0000, v115
	v_pk_add_f32 v[124:125], v[124:125], v[132:133]
	v_pk_add_f32 v[126:127], v[126:127], v[134:135]
	v_pk_add_f32 v[128:129], v[128:129], v[136:137]
	v_pk_add_f32 v[130:131], v[130:131], v[138:139]
	v_pk_fma_f32 v[132:133], v[148:149], v[124:125], v[132:133] neg_lo:[0,0,1] neg_hi:[0,0,1]
	v_pk_fma_f32 v[134:135], v[148:149], v[126:127], v[134:135] neg_lo:[0,0,1] neg_hi:[0,0,1]
	v_pk_fma_f32 v[136:137], v[148:149], v[128:129], v[136:137] neg_lo:[0,0,1] neg_hi:[0,0,1]
	v_pk_fma_f32 v[138:139], v[148:149], v[130:131], v[138:139] neg_lo:[0,0,1] neg_hi:[0,0,1]
	v_cvt_pk_bf16_f32 v140, v132, v133
	v_cvt_pk_bf16_f32 v141, v134, v135
	v_cvt_pk_bf16_f32 v142, v136, v137
	v_cvt_pk_bf16_f32 v143, v138, v139
	v_lshl_add_u64 v[150:151], v[224:225], 0, s[70:71]
	s_add_u32 s70, s70, 0x1000
	global_store_dwordx4 v[150:151], v[140:143], off
	v_cndmask_b32_e64 v144, v84, v52, s[68:69]
	v_cndmask_b32_e64 v145, v85, v53, s[68:69]
	v_cndmask_b32_e64 v146, v86, v54, s[68:69]
	v_cndmask_b32_e64 v147, v87, v55, s[68:69]
	v_lshlrev_b32_e32 v132, 16, v144
	v_and_b32_e32 v133, 0xffff0000, v144
	v_lshlrev_b32_e32 v134, 16, v145
	v_and_b32_e32 v135, 0xffff0000, v145
	v_lshlrev_b32_e32 v136, 16, v146
	v_and_b32_e32 v137, 0xffff0000, v146
	v_lshlrev_b32_e32 v138, 16, v147
	v_and_b32_e32 v139, 0xffff0000, v147
	v_pk_add_f32 v[124:125], v[124:125], v[132:133] neg_lo:[0,1] neg_hi:[0,1]
	v_pk_add_f32 v[126:127], v[126:127], v[134:135] neg_lo:[0,1] neg_hi:[0,1]
	v_pk_add_f32 v[128:129], v[128:129], v[136:137] neg_lo:[0,1] neg_hi:[0,1]
	v_pk_add_f32 v[130:131], v[130:131], v[138:139] neg_lo:[0,1] neg_hi:[0,1]
	s_waitcnt vmcnt(15)
; __device__ __forceinline__ float bf_lo(unsigned w) { return __uint_as_float(w << 16); }
; __device__ __forceinline__ float bf_hi(unsigned w) { return __uint_as_float(w & 0xffff0000u); }
; __device__ __forceinline__ unsigned pk2(float lo, float hi) { return f2bf(lo) | (f2bf(hi) << 16); }
; template <int W> __device__ __forceinline__ void pool_item(const bfu* u, bfu* pooled, int tb) {
;     ...
;     for (int k = 0; k < 8; ++k) {
;         const v4u c = r[W - 1 + k]; const int t = tb + k;
;         const float cv[8] = {pg8::bf_lo(c.x), pg8::bf_hi(c.x), pg8::bf_lo(c.y), pg8::bf_hi(c.y), pg8::bf_lo(c.z), pg8::bf_hi(c.z), pg8::bf_lo(c.w), pg8::bf_hi(c.w)};
; #pragma unroll
;         for (int e = 0; e < 8; ++e) a[e] += cv[e];
;         const float inv = 1.f / (float)((t + 1) < W ? (t + 1) : W);
;         v4u o; o.x = pk2(a[0] * inv - cv[0], a[1] * inv - cv[1]); o.y = pk2(a[2] * inv - cv[2], a[3] * inv - cv[3]); o.z = pk2(a[4] * inv - cv[4], a[5] * inv - cv[5]); o.w = pk2(a[6] * inv - cv[6], a[7] * inv - cv[7]);
;         *(v4u*)(pooled + (size_t)t * 2048) = o;
;         const v4u d = r[k];
;         a[0] -= pg8::bf_lo(d.x); a[1] -= pg8::bf_hi(d.x); a[2] -= pg8::bf_lo(d.y); a[3] -= pg8::bf_hi(d.y); a[4] -= pg8::bf_lo(d.z); a[5] -= pg8::bf_hi(d.z); a[6] -= pg8::bf_lo(d.w); a[7] -= pg8::bf_hi(d.w);
;     }
	v_lshlrev_b32_e32 v132, 16, v116
	v_and_b32_e32 v133, 0xffff0000, v116
	v_lshlrev_b32_e32 v134, 16, v117
	v_and_b32_e32 v135, 0xffff0000, v117
	v_lshlrev_b32_e32 v136, 16, v118
	v_and_b32_e32 v137, 0xffff0000, v118
	v_lshlrev_b32_e32 v138, 16, v119
	v_and_b32_e32 v139, 0xffff0000, v119
	v_pk_add_f32 v[124:125], v[124:125], v[132:133]
	v_pk_add_f32 v[126:127], v[126:127], v[134:135]
	v_pk_add_f32 v[128:129], v[128:129], v[136:137]
	v_pk_add_f32 v[130:131], v[130:131], v[138:139]
	v_pk_fma_f32 v[132:133], v[148:149], v[124:125], v[132:133] neg_lo:[0,0,1] neg_hi:[0,0,1]
	v_pk_fma_f32 v[134:135], v[148:149], v[126:127], v[134:135] neg_lo:[0,0,1] neg_hi:[0,0,1]
	v_pk_fma_f32 v[136:137], v[148:149], v[128:129], v[136:137] neg_lo:[0,0,1] neg_hi:[0,0,1]
	v_pk_fma_f32 v[138:139], v[148:149], v[130:131], v[138:139] neg_lo:[0,0,1] neg_hi:[0,0,1]
	v_cvt_pk_bf16_f32 v140, v132, v133
	v_cvt_pk_bf16_f32 v141, v134, v135
	v_cvt_pk_bf16_f32 v142, v136, v137
	v_cvt_pk_bf16_f32 v143, v138, v139
	v_lshl_add_u64 v[150:151], v[224:225], 0, s[70:71]
	s_add_u32 s70, s70, 0x1000
	global_store_dwordx4 v[150:151], v[140:143], off
	v_cndmask_b32_e64 v144, v88, v56, s[68:69]
	v_cndmask_b32_e64 v145, v89, v57, s[68:69]
	v_cndmask_b32_e64 v146, v90, v58, s[68:69]
	v_cndmask_b32_e64 v147, v91, v59, s[68:69]
	v_lshlrev_b32_e32 v132, 16, v144
	v_and_b32_e32 v133, 0xffff0000, v144
	v_lshlrev_b32_e32 v134, 16, v145
	v_and_b32_e32 v135, 0xffff0000, v145
	v_lshlrev_b32_e32 v136, 16, v146
	v_and_b32_e32 v137, 0xffff0000, v146
	v_lshlrev_b32_e32 v138, 16, v147
	v_and_b32_e32 v139, 0xffff0000, v147
	v_pk_add_f32 v[124:125], v[124:125], v[132:133] neg_lo:[0,1] neg_hi:[0,1]
	v_pk_add_f32 v[126:127], v[126:127], v[134:135] neg_lo:[0,1] neg_hi:[0,1]
	v_pk_add_f32 v[128:129], v[128:129], v[136:137] neg_lo:[0,1] neg_hi:[0,1]
	v_pk_add_f32 v[130:131], v[130:131], v[138:139] neg_lo:[0,1] neg_hi:[0,1]
	s_waitcnt vmcnt(15)
	v_lshlrev_b32_e32 v132, 16, v120
	v_and_b32_e32 v133, 0xffff0000, v120
	v_lshlrev_b32_e32 v134, 16, v121
	v_and_b32_e32 v135, 0xffff0000, v121
	v_lshlrev_b32_e32 v136, 16, v122
	v_and_b32_e32 v137, 0xffff0000, v122
	v_lshlrev_b32_e32 v138, 16, v123
	v_and_b32_e32 v139, 0xffff0000, v123
	v_pk_add_f32 v[124:125], v[124:125], v[132:133]
	v_pk_add_f32 v[126:127], v[126:127], v[134:135]
	v_pk_add_f32 v[128:129], v[128:129], v[136:137]
	v_pk_add_f32 v[130:131], v[130:131], v[138:139]
	v_pk_fma_f32 v[132:133], v[148:149], v[124:125], v[132:133] neg_lo:[0,0,1] neg_hi:[0,0,1]
	v_pk_fma_f32 v[134:135], v[148:149], v[126:127], v[134:135] neg_lo:[0,0,1] neg_hi:[0,0,1]
	v_pk_fma_f32 v[136:137], v[148:149], v[128:129], v[136:137] neg_lo:[0,0,1] neg_hi:[0,0,1]
	v_pk_fma_f32 v[138:139], v[148:149], v[130:131], v[138:139] neg_lo:[0,0,1] neg_hi:[0,0,1]
	v_cvt_pk_bf16_f32 v140, v132, v133
	v_cvt_pk_bf16_f32 v141, v134, v135
	v_cvt_pk_bf16_f32 v142, v136, v137
	v_cvt_pk_bf16_f32 v143, v138, v139
	v_lshl_add_u64 v[150:151], v[224:225], 0, s[70:71]
	s_add_u32 s70, s70, 0x1000
	global_store_dwordx4 v[150:151], v[140:143], off
	v_cndmask_b32_e64 v144, v92, v60, s[68:69]
	v_cndmask_b32_e64 v145, v93, v61, s[68:69]
	v_cndmask_b32_e64 v146, v94, v62, s[68:69]
	v_cndmask_b32_e64 v147, v95, v63, s[68:69]
	v_lshlrev_b32_e32 v132, 16, v144
	v_and_b32_e32 v133, 0xffff0000, v144
	v_lshlrev_b32_e32 v134, 16, v145
	v_and_b32_e32 v135, 0xffff0000, v145
	v_lshlrev_b32_e32 v136, 16, v146
	v_and_b32_e32 v137, 0xffff0000, v146
	v_lshlrev_b32_e32 v138, 16, v147
	v_and_b32_e32 v139, 0xffff0000, v147
	v_pk_add_f32 v[124:125], v[124:125], v[132:133] neg_lo:[0,1] neg_hi:[0,1]
	v_pk_add_f32 v[126:127], v[126:127], v[134:135] neg_lo:[0,1] neg_hi:[0,1]
	v_pk_add_f32 v[128:129], v[128:129], v[136:137] neg_lo:[0,1] neg_hi:[0,1]
	v_pk_add_f32 v[130:131], v[130:131], v[138:139] neg_lo:[0,1] neg_hi:[0,1]
	s_branch .Lpool_done
